# gMLP: zU rows of the unit read into L2 during the statistics phase (prefetch loads discarded) so group-loop u loads hit L2
# baseline (speedup 1.0000x reference)
; DI float bflo(unsigned w) { return __uint_as_float(w << 16); }
; DI float bfhi(unsigned w) { return __uint_as_float(w & 0xffff0000u); }
; DI void gmlp_unit(LAS char* lds, bf16_t* zU, const bf16_t* zV, const float* g_ln, const float* b_ln, const bf16_t* Wb, const float* b_sp, int R0, bool dummy = false) {
;     ...
;     { u32x4 rw[16];
; #pragma unroll
;       for (int i = 0; i < 16; ++i) rw[i] = *(const u32x4*)(zV + (size_t)(R0 + wid * 16 + i) * 512 + lane * 8);
; #pragma unroll
;       for (int i = 0; i < 16; ++i) { const int s = wid * 16 + i; const u32x4 w = rw[i];
;         const float v[8] = {bflo(w.x), bfhi(w.x), bflo(w.y), bfhi(w.y), bflo(w.z), bfhi(w.z), bflo(w.w), bfhi(w.w)};
;         float a = 0.f, q = 0.f;
; #pragma unroll
;         for (int e = 0; e < 8; ++e) { a += v[e]; q += v[e] * v[e]; }
;         a = wave_sum(a); q = wave_sum(q);
;         const float mu = a * (1.0f / 512.0f), var = fmaxf(q * (1.0f / 512.0f) - mu * mu, 0.f);
;         if (lane == 0) { St[2 * s] = mu; St[2 * s + 1] = __builtin_amdgcn_rsqf(var + EPSN); } } }
.LBB0_496:
	v_mov_b32_e32 v1, v232
	s_lshl_b32 s6, s2, 7
	v_readfirstlane_b32 s8, v1
	s_ashr_i32 s12, s8, 6
	s_and_b32 s9, s6, 0xff80
	s_lshl_b32 s6, s12, 4
	v_and_b32_e32 v66, 63, v1
	s_add_i32 s6, s6, s9
	v_lshlrev_b32_e32 v2, 4, v66
	v_mov_b32_e32 v3, v0
	s_ashr_i32 s7, s6, 31
	v_lshl_add_u64 v[2:3], s[88:89], 0, v[2:3]
	s_lshl_b64 s[10:11], s[6:7], 10
	v_lshl_add_u64 v[4:5], v[2:3], 0, s[10:11]
	s_mov_b32 s98, 0xfc000000
	s_mov_b32 s99, -1
	v_lshl_add_u64 v[86:87], v[4:5], 0, s[98:99]
	s_or_b32 s10, s6, 1
	s_ashr_i32 s11, s10, 31
	s_lshl_b64 s[10:11], s[10:11], 10
	v_lshl_add_u64 v[6:7], v[2:3], 0, s[10:11]
	s_or_b32 s10, s6, 2
	s_ashr_i32 s11, s10, 31
	s_lshl_b64 s[10:11], s[10:11], 10
	s_barrier
	global_load_dwordx4 v[62:65], v[4:5], off
	global_load_dwordx4 v[58:61], v[6:7], off
	v_lshl_add_u64 v[4:5], v[2:3], 0, s[10:11]
	s_or_b32 s10, s6, 3
	s_ashr_i32 s11, s10, 31
	s_lshl_b64 s[10:11], s[10:11], 10
	v_lshl_add_u64 v[6:7], v[2:3], 0, s[10:11]
	s_or_b32 s10, s6, 4
	s_ashr_i32 s11, s10, 31
	s_lshl_b64 s[10:11], s[10:11], 10
	global_load_dwordx4 v[54:57], v[4:5], off
	global_load_dwordx4 v[50:53], v[6:7], off
	v_lshl_add_u64 v[4:5], v[2:3], 0, s[10:11]
	s_or_b32 s10, s6, 5
	s_ashr_i32 s11, s10, 31
	s_lshl_b64 s[10:11], s[10:11], 10
	v_lshl_add_u64 v[6:7], v[2:3], 0, s[10:11]
	s_or_b32 s10, s6, 6
	s_ashr_i32 s11, s10, 31
	s_lshl_b64 s[10:11], s[10:11], 10
	global_load_dwordx4 v[46:49], v[4:5], off
	global_load_dwordx4 v[42:45], v[6:7], off
	v_lshl_add_u64 v[4:5], v[2:3], 0, s[10:11]
	s_or_b32 s10, s6, 7
	s_ashr_i32 s11, s10, 31
	s_lshl_b64 s[10:11], s[10:11], 10
	v_lshl_add_u64 v[6:7], v[2:3], 0, s[10:11]
	s_or_b32 s10, s6, 8
	s_ashr_i32 s11, s10, 31
	s_lshl_b64 s[10:11], s[10:11], 10
	global_load_dwordx4 v[38:41], v[4:5], off
	global_load_dwordx4 v[34:37], v[6:7], off
	v_lshl_add_u64 v[4:5], v[2:3], 0, s[10:11]
	s_or_b32 s10, s6, 9
	s_ashr_i32 s11, s10, 31
	s_lshl_b64 s[10:11], s[10:11], 10
	v_lshl_add_u64 v[6:7], v[2:3], 0, s[10:11]
	s_or_b32 s10, s6, 10
	s_ashr_i32 s11, s10, 31
	s_lshl_b64 s[10:11], s[10:11], 10
	global_load_dwordx4 v[30:33], v[4:5], off
	global_load_dwordx4 v[26:29], v[6:7], off
	v_lshl_add_u64 v[4:5], v[2:3], 0, s[10:11]
	s_or_b32 s10, s6, 11
	s_ashr_i32 s11, s10, 31
	s_lshl_b64 s[10:11], s[10:11], 10
	v_lshl_add_u64 v[6:7], v[2:3], 0, s[10:11]
	s_or_b32 s10, s6, 12
	s_ashr_i32 s11, s10, 31
	s_lshl_b64 s[10:11], s[10:11], 10
	global_load_dwordx4 v[22:25], v[4:5], off
	global_load_dwordx4 v[18:21], v[6:7], off
	v_lshl_add_u64 v[4:5], v[2:3], 0, s[10:11]
	s_or_b32 s10, s6, 13
	s_ashr_i32 s11, s10, 31
	s_lshl_b64 s[10:11], s[10:11], 10
	v_lshl_add_u64 v[6:7], v[2:3], 0, s[10:11]
	s_or_b32 s10, s6, 14
	s_or_b32 s6, s6, 15
	s_ashr_i32 s11, s10, 31
	s_ashr_i32 s7, s6, 31
	s_lshl_b64 s[10:11], s[10:11], 10
	s_lshl_b64 s[6:7], s[6:7], 10
	global_load_dwordx4 v[14:17], v[4:5], off
	global_load_dwordx4 v[10:13], v[6:7], off
	v_lshl_add_u64 v[4:5], v[2:3], 0, s[10:11]
	v_lshl_add_u64 v[2:3], v[2:3], 0, s[6:7]
	global_load_dwordx4 v[6:9], v[4:5], off
	s_nop 0
	global_load_dwordx4 v[2:5], v[2:3], off
	s_mov_b64 s[98:99], 0x1000
	global_load_dwordx4 v[82:85], v[86:87], off
	global_load_dwordx4 v[82:85], v[86:87], off offset:1024
	global_load_dwordx4 v[82:85], v[86:87], off offset:2048
	global_load_dwordx4 v[82:85], v[86:87], off offset:3072
	v_lshl_add_u64 v[86:87], v[86:87], 0, s[98:99]
	global_load_dwordx4 v[82:85], v[86:87], off
	global_load_dwordx4 v[82:85], v[86:87], off offset:1024
	global_load_dwordx4 v[82:85], v[86:87], off offset:2048
	global_load_dwordx4 v[82:85], v[86:87], off offset:3072
	v_lshl_add_u64 v[86:87], v[86:87], 0, s[98:99]
	global_load_dwordx4 v[82:85], v[86:87], off
	global_load_dwordx4 v[82:85], v[86:87], off offset:1024
	global_load_dwordx4 v[82:85], v[86:87], off offset:2048
	global_load_dwordx4 v[82:85], v[86:87], off offset:3072
	v_lshl_add_u64 v[86:87], v[86:87], 0, s[98:99]
	global_load_dwordx4 v[82:85], v[86:87], off
	global_load_dwordx4 v[82:85], v[86:87], off offset:1024
	global_load_dwordx4 v[82:85], v[86:87], off offset:2048
	global_load_dwordx4 v[82:85], v[86:87], off offset:3072
	v_cmp_eq_u32_e32 vcc, 0, v66
	s_lshl_b32 s10, s12, 7
	s_waitcnt vmcnt(31)
	v_lshlrev_b32_e32 v67, 16, v62
	v_and_b32_e32 v62, 0xffff0000, v62
	v_add_f32_e32 v71, 0, v67
	v_mul_f32_e32 v72, v62, v62
	v_lshlrev_b32_e32 v68, 16, v63
	v_add_f32_e32 v71, v71, v62
	v_fmac_f32_e32 v72, v67, v67
	v_and_b32_e32 v63, 0xffff0000, v63
	v_add_f32_e32 v62, v71, v68
	v_fmac_f32_e32 v72, v68, v68
	v_lshlrev_b32_e32 v69, 16, v64
	v_add_f32_e32 v62, v62, v63
	v_fmac_f32_e32 v72, v63, v63
	v_and_b32_e32 v64, 0xffff0000, v64
	v_add_f32_e32 v62, v62, v69
	v_fmac_f32_e32 v72, v69, v69
	v_lshlrev_b32_e32 v70, 16, v65
	v_add_f32_e32 v62, v62, v64
	v_fmac_f32_e32 v72, v64, v64
	v_and_b32_e32 v65, 0xffff0000, v65
	v_add_f32_e32 v62, v62, v70
	v_fmac_f32_e32 v72, v70, v70
	v_add_f32_e32 v62, v62, v65
	v_fmac_f32_e32 v72, v65, v65
	s_nop 0
	v_add_f32_dpp v62, v62, v62 row_ror:1 row_mask:0xf bank_mask:0xf bound_ctrl:1
	v_add_f32_dpp v64, v72, v72 row_ror:1 row_mask:0xf bank_mask:0xf bound_ctrl:1
	s_nop 0
	v_add_f32_dpp v62, v62, v62 row_ror:2 row_mask:0xf bank_mask:0xf bound_ctrl:1
	v_add_f32_dpp v64, v64, v64 row_ror:2 row_mask:0xf bank_mask:0xf bound_ctrl:1
	s_nop 0
	v_add_f32_dpp v62, v62, v62 row_ror:4 row_mask:0xf bank_mask:0xf bound_ctrl:1
	v_add_f32_dpp v64, v64, v64 row_ror:4 row_mask:0xf bank_mask:0xf bound_ctrl:1
	s_nop 0
	v_add_f32_dpp v62, v62, v62 row_ror:8 row_mask:0xf bank_mask:0xf bound_ctrl:1
	v_add_f32_dpp v64, v64, v64 row_ror:8 row_mask:0xf bank_mask:0xf bound_ctrl:1
	v_mov_b32_e32 v63, v62
	v_mov_b32_e32 v65, v64
	s_nop 0
	v_permlane16_swap_b32_e32 v62, v63
	v_permlane16_swap_b32_e32 v64, v65
	v_add_f32_e32 v62, v62, v63
	v_add_f32_e32 v64, v64, v65
	v_mov_b32_e32 v63, v62
	v_mov_b32_e32 v65, v64
	s_nop 0
	v_permlane32_swap_b32_e32 v62, v63
	v_permlane32_swap_b32_e32 v64, v65
	s_and_saveexec_b64 s[6:7], vcc
	s_cbranch_execz .LBB0_498
	v_add_f32_e32 v62, v62, v63
	v_mul_f32_e32 v62, 0x3b000000, v62
	v_add_f32_e32 v64, v64, v65
	v_mul_f32_e32 v63, v62, v62
	v_fma_f32 v63, v64, s4, -v63
	v_max_f32_e32 v63, 0, v63
	v_add_f32_e32 v63, 0x358637bd, v63
	v_rsq_f32_e32 v63, v63
	s_add_i32 s11, s10, 0
	s_add_i32 s11, s11, 0x12800
	v_mov_b32_e32 v64, s11
	ds_write_b64 v64, v[62:63]
; DI float bflo(unsigned w) { return __uint_as_float(w << 16); }
; DI float bfhi(unsigned w) { return __uint_as_float(w & 0xffff0000u); }
; DI void gmlp_unit(LAS char* lds, bf16_t* zU, const bf16_t* zV, const float* g_ln, const float* b_ln, const bf16_t* Wb, const float* b_sp, int R0, bool dummy = false) {
;     ...
;       for (int i = 0; i < 16; ++i) { const int s = wid * 16 + i; const u32x4 w = rw[i];
;         const float v[8] = {bflo(w.x), bfhi(w.x), bflo(w.y), bfhi(w.y), bflo(w.z), bfhi(w.z), bflo(w.w), bfhi(w.w)};
;         float a = 0.f, q = 0.f;
; #pragma unroll
;         for (int e = 0; e < 8; ++e) { a += v[e]; q += v[e] * v[e]; }
;         a = wave_sum(a); q = wave_sum(q);
;         const float mu = a * (1.0f / 512.0f), var = fmaxf(q * (1.0f / 512.0f) - mu * mu, 0.f);
;         if (lane == 0) { St[2 * s] = mu; St[2 * s + 1] = __builtin_amdgcn_rsqf(var + EPSN); } } }
.LBB0_498:
	s_or_b64 exec, exec, s[6:7]
	s_waitcnt vmcnt(30)
	v_lshlrev_b32_e32 v62, 16, v58
	v_and_b32_e32 v58, 0xffff0000, v58
	v_add_f32_e32 v67, 0, v62
	v_mul_f32_e32 v68, v58, v58
	v_lshlrev_b32_e32 v63, 16, v59
	v_add_f32_e32 v67, v67, v58
	v_fmac_f32_e32 v68, v62, v62
	v_and_b32_e32 v59, 0xffff0000, v59
	v_add_f32_e32 v58, v67, v63
	v_fmac_f32_e32 v68, v63, v63
	v_lshlrev_b32_e32 v64, 16, v60
	v_add_f32_e32 v58, v58, v59
	v_fmac_f32_e32 v68, v59, v59
	v_and_b32_e32 v60, 0xffff0000, v60
	v_add_f32_e32 v58, v58, v64
	v_fmac_f32_e32 v68, v64, v64
	v_lshlrev_b32_e32 v65, 16, v61
	v_add_f32_e32 v58, v58, v60
	v_fmac_f32_e32 v68, v60, v60
	v_and_b32_e32 v61, 0xffff0000, v61
	v_add_f32_e32 v58, v58, v65
	v_fmac_f32_e32 v68, v65, v65
	v_add_f32_e32 v58, v58, v61
	v_fmac_f32_e32 v68, v61, v61
	s_nop 0
	v_add_f32_dpp v58, v58, v58 row_ror:1 row_mask:0xf bank_mask:0xf bound_ctrl:1
	v_add_f32_dpp v60, v68, v68 row_ror:1 row_mask:0xf bank_mask:0xf bound_ctrl:1
	s_nop 0
	v_add_f32_dpp v58, v58, v58 row_ror:2 row_mask:0xf bank_mask:0xf bound_ctrl:1
	v_add_f32_dpp v60, v60, v60 row_ror:2 row_mask:0xf bank_mask:0xf bound_ctrl:1
	s_nop 0
	v_add_f32_dpp v58, v58, v58 row_ror:4 row_mask:0xf bank_mask:0xf bound_ctrl:1
	v_add_f32_dpp v60, v60, v60 row_ror:4 row_mask:0xf bank_mask:0xf bound_ctrl:1
	s_nop 0
	v_add_f32_dpp v58, v58, v58 row_ror:8 row_mask:0xf bank_mask:0xf bound_ctrl:1
	v_add_f32_dpp v60, v60, v60 row_ror:8 row_mask:0xf bank_mask:0xf bound_ctrl:1
	v_mov_b32_e32 v59, v58
	v_mov_b32_e32 v61, v60
	s_nop 0
	v_permlane16_swap_b32_e32 v58, v59
	v_permlane16_swap_b32_e32 v60, v61
	v_add_f32_e32 v58, v58, v59
	v_add_f32_e32 v60, v60, v61
	v_mov_b32_e32 v59, v58
	v_mov_b32_e32 v61, v60
	s_nop 0
	v_permlane32_swap_b32_e32 v58, v59
	v_permlane32_swap_b32_e32 v60, v61
	s_and_saveexec_b64 s[6:7], vcc
	s_cbranch_execz .LBB0_500
	v_add_f32_e32 v58, v58, v59
	v_mul_f32_e32 v58, 0x3b000000, v58
	v_add_f32_e32 v60, v60, v61
	v_mul_f32_e32 v59, v58, v58
	v_fma_f32 v59, v60, s4, -v59
	v_max_f32_e32 v59, 0, v59
	v_add_f32_e32 v59, 0x358637bd, v59
	v_rsq_f32_e32 v59, v59
	s_add_i32 s11, s10, 0
	s_add_i32 s11, s11, 0x12808
	v_mov_b32_e32 v60, s11
	ds_write_b64 v60, v[58:59]
.LBB0_500:
	s_or_b64 exec, exec, s[6:7]
	s_waitcnt vmcnt(29)
	v_lshlrev_b32_e32 v58, 16, v54
	v_and_b32_e32 v54, 0xffff0000, v54
	v_add_f32_e32 v62, 0, v58
	v_mul_f32_e32 v63, v54, v54
	v_lshlrev_b32_e32 v59, 16, v55
	v_add_f32_e32 v62, v62, v54
	v_fmac_f32_e32 v63, v58, v58
	v_and_b32_e32 v55, 0xffff0000, v55
	v_add_f32_e32 v54, v62, v59
	v_fmac_f32_e32 v63, v59, v59
	v_lshlrev_b32_e32 v60, 16, v56
	v_add_f32_e32 v54, v54, v55
	v_fmac_f32_e32 v63, v55, v55
	v_and_b32_e32 v56, 0xffff0000, v56
	v_add_f32_e32 v54, v54, v60
	v_fmac_f32_e32 v63, v60, v60
	v_lshlrev_b32_e32 v61, 16, v57
	v_add_f32_e32 v54, v54, v56
	v_fmac_f32_e32 v63, v56, v56
	v_and_b32_e32 v57, 0xffff0000, v57
	v_add_f32_e32 v54, v54, v61
	v_fmac_f32_e32 v63, v61, v61
	v_add_f32_e32 v54, v54, v57
	v_fmac_f32_e32 v63, v57, v57
	s_nop 0
	v_add_f32_dpp v54, v54, v54 row_ror:1 row_mask:0xf bank_mask:0xf bound_ctrl:1
	v_add_f32_dpp v56, v63, v63 row_ror:1 row_mask:0xf bank_mask:0xf bound_ctrl:1
	s_nop 0
	v_add_f32_dpp v54, v54, v54 row_ror:2 row_mask:0xf bank_mask:0xf bound_ctrl:1
	v_add_f32_dpp v56, v56, v56 row_ror:2 row_mask:0xf bank_mask:0xf bound_ctrl:1
	s_nop 0
	v_add_f32_dpp v54, v54, v54 row_ror:4 row_mask:0xf bank_mask:0xf bound_ctrl:1
	v_add_f32_dpp v56, v56, v56 row_ror:4 row_mask:0xf bank_mask:0xf bound_ctrl:1
	s_nop 0
	v_add_f32_dpp v54, v54, v54 row_ror:8 row_mask:0xf bank_mask:0xf bound_ctrl:1
	v_add_f32_dpp v56, v56, v56 row_ror:8 row_mask:0xf bank_mask:0xf bound_ctrl:1
	v_mov_b32_e32 v55, v54
	v_mov_b32_e32 v57, v56
	s_nop 0
	v_permlane16_swap_b32_e32 v54, v55
	v_permlane16_swap_b32_e32 v56, v57
	v_add_f32_e32 v54, v54, v55
	v_add_f32_e32 v56, v56, v57
	v_mov_b32_e32 v55, v54
	v_mov_b32_e32 v57, v56
	s_nop 0
	v_permlane32_swap_b32_e32 v54, v55
	v_permlane32_swap_b32_e32 v56, v57
	s_and_saveexec_b64 s[6:7], vcc
	s_cbranch_execz .LBB0_502
	v_add_f32_e32 v54, v54, v55
	v_mul_f32_e32 v54, 0x3b000000, v54
	v_add_f32_e32 v56, v56, v57
	v_mul_f32_e32 v55, v54, v54
	v_fma_f32 v55, v56, s4, -v55
	v_max_f32_e32 v55, 0, v55
	v_add_f32_e32 v55, 0x358637bd, v55
	v_rsq_f32_e32 v55, v55
	s_add_i32 s11, s10, 0
	s_add_i32 s11, s11, 0x12810
	v_mov_b32_e32 v56, s11
	ds_write_b64 v56, v[54:55]
.LBB0_502:
	s_or_b64 exec, exec, s[6:7]
	s_waitcnt vmcnt(28)
	v_lshlrev_b32_e32 v54, 16, v50
	v_and_b32_e32 v50, 0xffff0000, v50
	v_add_f32_e32 v58, 0, v54
	v_mul_f32_e32 v59, v50, v50
	v_lshlrev_b32_e32 v55, 16, v51
	v_add_f32_e32 v58, v58, v50
	v_fmac_f32_e32 v59, v54, v54
	v_and_b32_e32 v51, 0xffff0000, v51
	v_add_f32_e32 v50, v58, v55
	v_fmac_f32_e32 v59, v55, v55
	v_lshlrev_b32_e32 v56, 16, v52
	v_add_f32_e32 v50, v50, v51
	v_fmac_f32_e32 v59, v51, v51
	v_and_b32_e32 v52, 0xffff0000, v52
	v_add_f32_e32 v50, v50, v56
	v_fmac_f32_e32 v59, v56, v56
	v_lshlrev_b32_e32 v57, 16, v53
	v_add_f32_e32 v50, v50, v52
	v_fmac_f32_e32 v59, v52, v52
	v_and_b32_e32 v53, 0xffff0000, v53
	v_add_f32_e32 v50, v50, v57
	v_fmac_f32_e32 v59, v57, v57
	v_add_f32_e32 v50, v50, v53
	v_fmac_f32_e32 v59, v53, v53
	s_nop 0
	v_add_f32_dpp v50, v50, v50 row_ror:1 row_mask:0xf bank_mask:0xf bound_ctrl:1
	v_add_f32_dpp v52, v59, v59 row_ror:1 row_mask:0xf bank_mask:0xf bound_ctrl:1
	s_nop 0
	v_add_f32_dpp v50, v50, v50 row_ror:2 row_mask:0xf bank_mask:0xf bound_ctrl:1
	v_add_f32_dpp v52, v52, v52 row_ror:2 row_mask:0xf bank_mask:0xf bound_ctrl:1
	s_nop 0
	v_add_f32_dpp v50, v50, v50 row_ror:4 row_mask:0xf bank_mask:0xf bound_ctrl:1
	v_add_f32_dpp v52, v52, v52 row_ror:4 row_mask:0xf bank_mask:0xf bound_ctrl:1
	s_nop 0
	v_add_f32_dpp v50, v50, v50 row_ror:8 row_mask:0xf bank_mask:0xf bound_ctrl:1
	v_add_f32_dpp v52, v52, v52 row_ror:8 row_mask:0xf bank_mask:0xf bound_ctrl:1
	v_mov_b32_e32 v51, v50
	v_mov_b32_e32 v53, v52
	s_nop 0
	v_permlane16_swap_b32_e32 v50, v51
	v_permlane16_swap_b32_e32 v52, v53
	v_add_f32_e32 v50, v50, v51
	v_add_f32_e32 v52, v52, v53
	v_mov_b32_e32 v51, v50
	v_mov_b32_e32 v53, v52
	s_nop 0
	v_permlane32_swap_b32_e32 v50, v51
	v_permlane32_swap_b32_e32 v52, v53
	s_and_saveexec_b64 s[6:7], vcc
	s_cbranch_execz .LBB0_504
	v_add_f32_e32 v50, v50, v51
	v_mul_f32_e32 v50, 0x3b000000, v50
	v_add_f32_e32 v52, v52, v53
	v_mul_f32_e32 v51, v50, v50
	v_fma_f32 v51, v52, s4, -v51
	v_max_f32_e32 v51, 0, v51
	v_add_f32_e32 v51, 0x358637bd, v51
	v_rsq_f32_e32 v51, v51
	s_add_i32 s11, s10, 0
	s_add_i32 s11, s11, 0x12818
	v_mov_b32_e32 v52, s11
	ds_write_b64 v52, v[50:51]
; DI float bflo(unsigned w) { return __uint_as_float(w << 16); }
; DI float bfhi(unsigned w) { return __uint_as_float(w & 0xffff0000u); }
; DI void gmlp_unit(LAS char* lds, bf16_t* zU, const bf16_t* zV, const float* g_ln, const float* b_ln, const bf16_t* Wb, const float* b_sp, int R0, bool dummy = false) {
;     ...
;       for (int i = 0; i < 16; ++i) { const int s = wid * 16 + i; const u32x4 w = rw[i];
;         const float v[8] = {bflo(w.x), bfhi(w.x), bflo(w.y), bfhi(w.y), bflo(w.z), bfhi(w.z), bflo(w.w), bfhi(w.w)};
;         float a = 0.f, q = 0.f;
; #pragma unroll
;         for (int e = 0; e < 8; ++e) { a += v[e]; q += v[e] * v[e]; }
;         a = wave_sum(a); q = wave_sum(q);
;         const float mu = a * (1.0f / 512.0f), var = fmaxf(q * (1.0f / 512.0f) - mu * mu, 0.f);
;         if (lane == 0) { St[2 * s] = mu; St[2 * s + 1] = __builtin_amdgcn_rsqf(var + EPSN); } } }
.LBB0_504:
	s_or_b64 exec, exec, s[6:7]
	s_waitcnt vmcnt(27)
	v_lshlrev_b32_e32 v50, 16, v46
	v_and_b32_e32 v46, 0xffff0000, v46
	v_add_f32_e32 v54, 0, v50
	v_mul_f32_e32 v55, v46, v46
	v_lshlrev_b32_e32 v51, 16, v47
	v_add_f32_e32 v54, v54, v46
	v_fmac_f32_e32 v55, v50, v50
	v_and_b32_e32 v47, 0xffff0000, v47
	v_add_f32_e32 v46, v54, v51
	v_fmac_f32_e32 v55, v51, v51
	v_lshlrev_b32_e32 v52, 16, v48
	v_add_f32_e32 v46, v46, v47
	v_fmac_f32_e32 v55, v47, v47
	v_and_b32_e32 v48, 0xffff0000, v48
	v_add_f32_e32 v46, v46, v52
	v_fmac_f32_e32 v55, v52, v52
	v_lshlrev_b32_e32 v53, 16, v49
	v_add_f32_e32 v46, v46, v48
	v_fmac_f32_e32 v55, v48, v48
	v_and_b32_e32 v49, 0xffff0000, v49
	v_add_f32_e32 v46, v46, v53
	v_fmac_f32_e32 v55, v53, v53
	v_add_f32_e32 v46, v46, v49
	v_fmac_f32_e32 v55, v49, v49
	s_nop 0
	v_add_f32_dpp v46, v46, v46 row_ror:1 row_mask:0xf bank_mask:0xf bound_ctrl:1
	v_add_f32_dpp v48, v55, v55 row_ror:1 row_mask:0xf bank_mask:0xf bound_ctrl:1
	s_nop 0
	v_add_f32_dpp v46, v46, v46 row_ror:2 row_mask:0xf bank_mask:0xf bound_ctrl:1
	v_add_f32_dpp v48, v48, v48 row_ror:2 row_mask:0xf bank_mask:0xf bound_ctrl:1
	s_nop 0
	v_add_f32_dpp v46, v46, v46 row_ror:4 row_mask:0xf bank_mask:0xf bound_ctrl:1
	v_add_f32_dpp v48, v48, v48 row_ror:4 row_mask:0xf bank_mask:0xf bound_ctrl:1
	s_nop 0
	v_add_f32_dpp v46, v46, v46 row_ror:8 row_mask:0xf bank_mask:0xf bound_ctrl:1
	v_add_f32_dpp v48, v48, v48 row_ror:8 row_mask:0xf bank_mask:0xf bound_ctrl:1
	v_mov_b32_e32 v47, v46
	v_mov_b32_e32 v49, v48
	s_nop 0
	v_permlane16_swap_b32_e32 v46, v47
	v_permlane16_swap_b32_e32 v48, v49
	v_add_f32_e32 v46, v46, v47
	v_add_f32_e32 v48, v48, v49
	v_mov_b32_e32 v47, v46
	v_mov_b32_e32 v49, v48
	s_nop 0
	v_permlane32_swap_b32_e32 v46, v47
	v_permlane32_swap_b32_e32 v48, v49
	s_and_saveexec_b64 s[6:7], vcc
	s_cbranch_execz .LBB0_506
	v_add_f32_e32 v46, v46, v47
	v_mul_f32_e32 v46, 0x3b000000, v46
	v_add_f32_e32 v48, v48, v49
	v_mul_f32_e32 v47, v46, v46
	v_fma_f32 v47, v48, s4, -v47
	v_max_f32_e32 v47, 0, v47
	v_add_f32_e32 v47, 0x358637bd, v47
	v_rsq_f32_e32 v47, v47
	s_add_i32 s11, s10, 0
	s_add_i32 s11, s11, 0x12820
	v_mov_b32_e32 v48, s11
	ds_write_b64 v48, v[46:47]
.LBB0_506:
	s_or_b64 exec, exec, s[6:7]
	s_waitcnt vmcnt(26)
	v_lshlrev_b32_e32 v46, 16, v42
	v_and_b32_e32 v42, 0xffff0000, v42
	v_add_f32_e32 v50, 0, v46
	v_mul_f32_e32 v51, v42, v42
	v_lshlrev_b32_e32 v47, 16, v43
	v_add_f32_e32 v50, v50, v42
	v_fmac_f32_e32 v51, v46, v46
	v_and_b32_e32 v43, 0xffff0000, v43
	v_add_f32_e32 v42, v50, v47
	v_fmac_f32_e32 v51, v47, v47
	v_lshlrev_b32_e32 v48, 16, v44
	v_add_f32_e32 v42, v42, v43
	v_fmac_f32_e32 v51, v43, v43
	v_and_b32_e32 v44, 0xffff0000, v44
	v_add_f32_e32 v42, v42, v48
	v_fmac_f32_e32 v51, v48, v48
	v_lshlrev_b32_e32 v49, 16, v45
	v_add_f32_e32 v42, v42, v44
	v_fmac_f32_e32 v51, v44, v44
	v_and_b32_e32 v45, 0xffff0000, v45
	v_add_f32_e32 v42, v42, v49
	v_fmac_f32_e32 v51, v49, v49
	v_add_f32_e32 v42, v42, v45
	v_fmac_f32_e32 v51, v45, v45
	s_nop 0
	v_add_f32_dpp v42, v42, v42 row_ror:1 row_mask:0xf bank_mask:0xf bound_ctrl:1
	v_add_f32_dpp v44, v51, v51 row_ror:1 row_mask:0xf bank_mask:0xf bound_ctrl:1
	s_nop 0
	v_add_f32_dpp v42, v42, v42 row_ror:2 row_mask:0xf bank_mask:0xf bound_ctrl:1
	v_add_f32_dpp v44, v44, v44 row_ror:2 row_mask:0xf bank_mask:0xf bound_ctrl:1
	s_nop 0
	v_add_f32_dpp v42, v42, v42 row_ror:4 row_mask:0xf bank_mask:0xf bound_ctrl:1
	v_add_f32_dpp v44, v44, v44 row_ror:4 row_mask:0xf bank_mask:0xf bound_ctrl:1
	s_nop 0
	v_add_f32_dpp v42, v42, v42 row_ror:8 row_mask:0xf bank_mask:0xf bound_ctrl:1
	v_add_f32_dpp v44, v44, v44 row_ror:8 row_mask:0xf bank_mask:0xf bound_ctrl:1
	v_mov_b32_e32 v43, v42
	v_mov_b32_e32 v45, v44
	s_nop 0
	v_permlane16_swap_b32_e32 v42, v43
	v_permlane16_swap_b32_e32 v44, v45
	v_add_f32_e32 v42, v42, v43
	v_add_f32_e32 v44, v44, v45
	v_mov_b32_e32 v43, v42
	v_mov_b32_e32 v45, v44
	s_nop 0
	v_permlane32_swap_b32_e32 v42, v43
	v_permlane32_swap_b32_e32 v44, v45
	s_and_saveexec_b64 s[6:7], vcc
	s_cbranch_execz .LBB0_508
	v_add_f32_e32 v42, v42, v43
	v_mul_f32_e32 v42, 0x3b000000, v42
	v_add_f32_e32 v44, v44, v45
	v_mul_f32_e32 v43, v42, v42
	v_fma_f32 v43, v44, s4, -v43
	v_max_f32_e32 v43, 0, v43
	v_add_f32_e32 v43, 0x358637bd, v43
	v_rsq_f32_e32 v43, v43
	s_add_i32 s11, s10, 0
	s_add_i32 s11, s11, 0x12828
	v_mov_b32_e32 v44, s11
	ds_write_b64 v44, v[42:43]
.LBB0_508:
	s_or_b64 exec, exec, s[6:7]
	s_waitcnt vmcnt(25)
	v_lshlrev_b32_e32 v42, 16, v38
	v_and_b32_e32 v38, 0xffff0000, v38
	v_add_f32_e32 v46, 0, v42
	v_mul_f32_e32 v47, v38, v38
	v_lshlrev_b32_e32 v43, 16, v39
	v_add_f32_e32 v46, v46, v38
	v_fmac_f32_e32 v47, v42, v42
	v_and_b32_e32 v39, 0xffff0000, v39
	v_add_f32_e32 v38, v46, v43
	v_fmac_f32_e32 v47, v43, v43
	v_lshlrev_b32_e32 v44, 16, v40
	v_add_f32_e32 v38, v38, v39
	v_fmac_f32_e32 v47, v39, v39
	v_and_b32_e32 v40, 0xffff0000, v40
	v_add_f32_e32 v38, v38, v44
	v_fmac_f32_e32 v47, v44, v44
	v_lshlrev_b32_e32 v45, 16, v41
	v_add_f32_e32 v38, v38, v40
	v_fmac_f32_e32 v47, v40, v40
	v_and_b32_e32 v41, 0xffff0000, v41
	v_add_f32_e32 v38, v38, v45
	v_fmac_f32_e32 v47, v45, v45
	v_add_f32_e32 v38, v38, v41
	v_fmac_f32_e32 v47, v41, v41
	s_nop 0
	v_add_f32_dpp v38, v38, v38 row_ror:1 row_mask:0xf bank_mask:0xf bound_ctrl:1
	v_add_f32_dpp v40, v47, v47 row_ror:1 row_mask:0xf bank_mask:0xf bound_ctrl:1
	s_nop 0
	v_add_f32_dpp v38, v38, v38 row_ror:2 row_mask:0xf bank_mask:0xf bound_ctrl:1
	v_add_f32_dpp v40, v40, v40 row_ror:2 row_mask:0xf bank_mask:0xf bound_ctrl:1
	s_nop 0
	v_add_f32_dpp v38, v38, v38 row_ror:4 row_mask:0xf bank_mask:0xf bound_ctrl:1
	v_add_f32_dpp v40, v40, v40 row_ror:4 row_mask:0xf bank_mask:0xf bound_ctrl:1
	s_nop 0
	v_add_f32_dpp v38, v38, v38 row_ror:8 row_mask:0xf bank_mask:0xf bound_ctrl:1
	v_add_f32_dpp v40, v40, v40 row_ror:8 row_mask:0xf bank_mask:0xf bound_ctrl:1
	v_mov_b32_e32 v39, v38
	v_mov_b32_e32 v41, v40
	s_nop 0
	v_permlane16_swap_b32_e32 v38, v39
	v_permlane16_swap_b32_e32 v40, v41
	v_add_f32_e32 v38, v38, v39
	v_add_f32_e32 v40, v40, v41
	v_mov_b32_e32 v39, v38
	v_mov_b32_e32 v41, v40
	s_nop 0
	v_permlane32_swap_b32_e32 v38, v39
	v_permlane32_swap_b32_e32 v40, v41
	s_and_saveexec_b64 s[6:7], vcc
	s_cbranch_execz .LBB0_510
	v_add_f32_e32 v38, v38, v39
	v_mul_f32_e32 v38, 0x3b000000, v38
	v_add_f32_e32 v40, v40, v41
	v_mul_f32_e32 v39, v38, v38
	v_fma_f32 v39, v40, s4, -v39
	v_max_f32_e32 v39, 0, v39
	v_add_f32_e32 v39, 0x358637bd, v39
	v_rsq_f32_e32 v39, v39
	s_add_i32 s11, s10, 0
	s_add_i32 s11, s11, 0x12830
	v_mov_b32_e32 v40, s11
	ds_write_b64 v40, v[38:39]
; DI float bflo(unsigned w) { return __uint_as_float(w << 16); }
; DI float bfhi(unsigned w) { return __uint_as_float(w & 0xffff0000u); }
; DI void gmlp_unit(LAS char* lds, bf16_t* zU, const bf16_t* zV, const float* g_ln, const float* b_ln, const bf16_t* Wb, const float* b_sp, int R0, bool dummy = false) {
;     ...
;       for (int i = 0; i < 16; ++i) { const int s = wid * 16 + i; const u32x4 w = rw[i];
;         const float v[8] = {bflo(w.x), bfhi(w.x), bflo(w.y), bfhi(w.y), bflo(w.z), bfhi(w.z), bflo(w.w), bfhi(w.w)};
;         float a = 0.f, q = 0.f;
; #pragma unroll
;         for (int e = 0; e < 8; ++e) { a += v[e]; q += v[e] * v[e]; }
;         a = wave_sum(a); q = wave_sum(q);
;         const float mu = a * (1.0f / 512.0f), var = fmaxf(q * (1.0f / 512.0f) - mu * mu, 0.f);
;         if (lane == 0) { St[2 * s] = mu; St[2 * s + 1] = __builtin_amdgcn_rsqf(var + EPSN); } } }
.LBB0_510:
	s_or_b64 exec, exec, s[6:7]
	s_waitcnt vmcnt(24)
	v_lshlrev_b32_e32 v38, 16, v34
	v_and_b32_e32 v34, 0xffff0000, v34
	v_add_f32_e32 v42, 0, v38
	v_mul_f32_e32 v43, v34, v34
	v_lshlrev_b32_e32 v39, 16, v35
	v_add_f32_e32 v42, v42, v34
	v_fmac_f32_e32 v43, v38, v38
	v_and_b32_e32 v35, 0xffff0000, v35
	v_add_f32_e32 v34, v42, v39
	v_fmac_f32_e32 v43, v39, v39
	v_lshlrev_b32_e32 v40, 16, v36
	v_add_f32_e32 v34, v34, v35
	v_fmac_f32_e32 v43, v35, v35
	v_and_b32_e32 v36, 0xffff0000, v36
	v_add_f32_e32 v34, v34, v40
	v_fmac_f32_e32 v43, v40, v40
	v_lshlrev_b32_e32 v41, 16, v37
	v_add_f32_e32 v34, v34, v36
	v_fmac_f32_e32 v43, v36, v36
	v_and_b32_e32 v37, 0xffff0000, v37
	v_add_f32_e32 v34, v34, v41
	v_fmac_f32_e32 v43, v41, v41
	v_add_f32_e32 v34, v34, v37
	v_fmac_f32_e32 v43, v37, v37
	s_nop 0
	v_add_f32_dpp v34, v34, v34 row_ror:1 row_mask:0xf bank_mask:0xf bound_ctrl:1
	v_add_f32_dpp v36, v43, v43 row_ror:1 row_mask:0xf bank_mask:0xf bound_ctrl:1
	s_nop 0
	v_add_f32_dpp v34, v34, v34 row_ror:2 row_mask:0xf bank_mask:0xf bound_ctrl:1
	v_add_f32_dpp v36, v36, v36 row_ror:2 row_mask:0xf bank_mask:0xf bound_ctrl:1
	s_nop 0
	v_add_f32_dpp v34, v34, v34 row_ror:4 row_mask:0xf bank_mask:0xf bound_ctrl:1
	v_add_f32_dpp v36, v36, v36 row_ror:4 row_mask:0xf bank_mask:0xf bound_ctrl:1
	s_nop 0
	v_add_f32_dpp v34, v34, v34 row_ror:8 row_mask:0xf bank_mask:0xf bound_ctrl:1
	v_add_f32_dpp v36, v36, v36 row_ror:8 row_mask:0xf bank_mask:0xf bound_ctrl:1
	v_mov_b32_e32 v35, v34
	v_mov_b32_e32 v37, v36
	s_nop 0
	v_permlane16_swap_b32_e32 v34, v35
	v_permlane16_swap_b32_e32 v36, v37
	v_add_f32_e32 v34, v34, v35
	v_add_f32_e32 v36, v36, v37
	v_mov_b32_e32 v35, v34
	v_mov_b32_e32 v37, v36
	s_nop 0
	v_permlane32_swap_b32_e32 v34, v35
	v_permlane32_swap_b32_e32 v36, v37
	s_and_saveexec_b64 s[6:7], vcc
	s_cbranch_execz .LBB0_512
	v_add_f32_e32 v34, v34, v35
	v_mul_f32_e32 v34, 0x3b000000, v34
	v_add_f32_e32 v36, v36, v37
	v_mul_f32_e32 v35, v34, v34
	v_fma_f32 v35, v36, s4, -v35
	v_max_f32_e32 v35, 0, v35
	v_add_f32_e32 v35, 0x358637bd, v35
	v_rsq_f32_e32 v35, v35
	s_add_i32 s11, s10, 0
	s_add_i32 s11, s11, 0x12838
	v_mov_b32_e32 v36, s11
	ds_write_b64 v36, v[34:35]
.LBB0_512:
	s_or_b64 exec, exec, s[6:7]
	s_waitcnt vmcnt(23)
	v_lshlrev_b32_e32 v34, 16, v30
	v_and_b32_e32 v30, 0xffff0000, v30
	v_add_f32_e32 v38, 0, v34
	v_mul_f32_e32 v39, v30, v30
	v_lshlrev_b32_e32 v35, 16, v31
	v_add_f32_e32 v38, v38, v30
	v_fmac_f32_e32 v39, v34, v34
	v_and_b32_e32 v31, 0xffff0000, v31
	v_add_f32_e32 v30, v38, v35
	v_fmac_f32_e32 v39, v35, v35
	v_lshlrev_b32_e32 v36, 16, v32
	v_add_f32_e32 v30, v30, v31
	v_fmac_f32_e32 v39, v31, v31
	v_and_b32_e32 v32, 0xffff0000, v32
	v_add_f32_e32 v30, v30, v36
	v_fmac_f32_e32 v39, v36, v36
	v_lshlrev_b32_e32 v37, 16, v33
	v_add_f32_e32 v30, v30, v32
	v_fmac_f32_e32 v39, v32, v32
	v_and_b32_e32 v33, 0xffff0000, v33
	v_add_f32_e32 v30, v30, v37
	v_fmac_f32_e32 v39, v37, v37
	v_add_f32_e32 v30, v30, v33
	v_fmac_f32_e32 v39, v33, v33
	s_nop 0
	v_add_f32_dpp v30, v30, v30 row_ror:1 row_mask:0xf bank_mask:0xf bound_ctrl:1
	v_add_f32_dpp v32, v39, v39 row_ror:1 row_mask:0xf bank_mask:0xf bound_ctrl:1
	s_nop 0
	v_add_f32_dpp v30, v30, v30 row_ror:2 row_mask:0xf bank_mask:0xf bound_ctrl:1
	v_add_f32_dpp v32, v32, v32 row_ror:2 row_mask:0xf bank_mask:0xf bound_ctrl:1
	s_nop 0
	v_add_f32_dpp v30, v30, v30 row_ror:4 row_mask:0xf bank_mask:0xf bound_ctrl:1
	v_add_f32_dpp v32, v32, v32 row_ror:4 row_mask:0xf bank_mask:0xf bound_ctrl:1
	s_nop 0
	v_add_f32_dpp v30, v30, v30 row_ror:8 row_mask:0xf bank_mask:0xf bound_ctrl:1
	v_add_f32_dpp v32, v32, v32 row_ror:8 row_mask:0xf bank_mask:0xf bound_ctrl:1
	v_mov_b32_e32 v31, v30
	v_mov_b32_e32 v33, v32
	s_nop 0
	v_permlane16_swap_b32_e32 v30, v31
	v_permlane16_swap_b32_e32 v32, v33
	v_add_f32_e32 v30, v30, v31
	v_add_f32_e32 v32, v32, v33
	v_mov_b32_e32 v31, v30
	v_mov_b32_e32 v33, v32
	s_nop 0
	v_permlane32_swap_b32_e32 v30, v31
	v_permlane32_swap_b32_e32 v32, v33
	s_and_saveexec_b64 s[6:7], vcc
	s_cbranch_execz .LBB0_514
	v_add_f32_e32 v30, v30, v31
	v_mul_f32_e32 v30, 0x3b000000, v30
	v_add_f32_e32 v32, v32, v33
	v_mul_f32_e32 v31, v30, v30
	v_fma_f32 v31, v32, s4, -v31
	v_max_f32_e32 v31, 0, v31
	v_add_f32_e32 v31, 0x358637bd, v31
	v_rsq_f32_e32 v31, v31
	s_add_i32 s11, s10, 0
	s_add_i32 s11, s11, 0x12840
	v_mov_b32_e32 v32, s11
	ds_write_b64 v32, v[30:31]
.LBB0_514:
	s_or_b64 exec, exec, s[6:7]
	s_waitcnt vmcnt(22)
	v_lshlrev_b32_e32 v30, 16, v26
	v_and_b32_e32 v26, 0xffff0000, v26
	v_add_f32_e32 v34, 0, v30
	v_mul_f32_e32 v35, v26, v26
	v_lshlrev_b32_e32 v31, 16, v27
	v_add_f32_e32 v34, v34, v26
	v_fmac_f32_e32 v35, v30, v30
	v_and_b32_e32 v27, 0xffff0000, v27
	v_add_f32_e32 v26, v34, v31
	v_fmac_f32_e32 v35, v31, v31
	v_lshlrev_b32_e32 v32, 16, v28
	v_add_f32_e32 v26, v26, v27
	v_fmac_f32_e32 v35, v27, v27
	v_and_b32_e32 v28, 0xffff0000, v28
	v_add_f32_e32 v26, v26, v32
	v_fmac_f32_e32 v35, v32, v32
	v_lshlrev_b32_e32 v33, 16, v29
	v_add_f32_e32 v26, v26, v28
	v_fmac_f32_e32 v35, v28, v28
	v_and_b32_e32 v29, 0xffff0000, v29
	v_add_f32_e32 v26, v26, v33
	v_fmac_f32_e32 v35, v33, v33
	v_add_f32_e32 v26, v26, v29
	v_fmac_f32_e32 v35, v29, v29
	s_nop 0
	v_add_f32_dpp v26, v26, v26 row_ror:1 row_mask:0xf bank_mask:0xf bound_ctrl:1
	v_add_f32_dpp v28, v35, v35 row_ror:1 row_mask:0xf bank_mask:0xf bound_ctrl:1
	s_nop 0
	v_add_f32_dpp v26, v26, v26 row_ror:2 row_mask:0xf bank_mask:0xf bound_ctrl:1
	v_add_f32_dpp v28, v28, v28 row_ror:2 row_mask:0xf bank_mask:0xf bound_ctrl:1
	s_nop 0
	v_add_f32_dpp v26, v26, v26 row_ror:4 row_mask:0xf bank_mask:0xf bound_ctrl:1
	v_add_f32_dpp v28, v28, v28 row_ror:4 row_mask:0xf bank_mask:0xf bound_ctrl:1
	s_nop 0
	v_add_f32_dpp v26, v26, v26 row_ror:8 row_mask:0xf bank_mask:0xf bound_ctrl:1
	v_add_f32_dpp v28, v28, v28 row_ror:8 row_mask:0xf bank_mask:0xf bound_ctrl:1
	v_mov_b32_e32 v27, v26
	v_mov_b32_e32 v29, v28
	s_nop 0
	v_permlane16_swap_b32_e32 v26, v27
	v_permlane16_swap_b32_e32 v28, v29
	v_add_f32_e32 v26, v26, v27
	v_add_f32_e32 v28, v28, v29
	v_mov_b32_e32 v27, v26
	v_mov_b32_e32 v29, v28
	s_nop 0
	v_permlane32_swap_b32_e32 v26, v27
	v_permlane32_swap_b32_e32 v28, v29
	s_and_saveexec_b64 s[6:7], vcc
	s_cbranch_execz .LBB0_516
	v_add_f32_e32 v26, v26, v27
	v_mul_f32_e32 v26, 0x3b000000, v26
	v_add_f32_e32 v28, v28, v29
	v_mul_f32_e32 v27, v26, v26
	v_fma_f32 v27, v28, s4, -v27
	v_max_f32_e32 v27, 0, v27
	v_add_f32_e32 v27, 0x358637bd, v27
	v_rsq_f32_e32 v27, v27
	s_add_i32 s11, s10, 0
	s_add_i32 s11, s11, 0x12848
	v_mov_b32_e32 v28, s11
	ds_write_b64 v28, v[26:27]
; DI float bflo(unsigned w) { return __uint_as_float(w << 16); }
; DI float bfhi(unsigned w) { return __uint_as_float(w & 0xffff0000u); }
; DI void gmlp_unit(LAS char* lds, bf16_t* zU, const bf16_t* zV, const float* g_ln, const float* b_ln, const bf16_t* Wb, const float* b_sp, int R0, bool dummy = false) {
;     ...
;       for (int i = 0; i < 16; ++i) { const int s = wid * 16 + i; const u32x4 w = rw[i];
;         const float v[8] = {bflo(w.x), bfhi(w.x), bflo(w.y), bfhi(w.y), bflo(w.z), bfhi(w.z), bflo(w.w), bfhi(w.w)};
;         float a = 0.f, q = 0.f;
; #pragma unroll
;         for (int e = 0; e < 8; ++e) { a += v[e]; q += v[e] * v[e]; }
;         a = wave_sum(a); q = wave_sum(q);
;         const float mu = a * (1.0f / 512.0f), var = fmaxf(q * (1.0f / 512.0f) - mu * mu, 0.f);
;         if (lane == 0) { St[2 * s] = mu; St[2 * s + 1] = __builtin_amdgcn_rsqf(var + EPSN); } } }
.LBB0_516:
	s_or_b64 exec, exec, s[6:7]
	s_waitcnt vmcnt(21)
	v_lshlrev_b32_e32 v26, 16, v22
	v_and_b32_e32 v22, 0xffff0000, v22
	v_add_f32_e32 v30, 0, v26
	v_mul_f32_e32 v31, v22, v22
	v_lshlrev_b32_e32 v27, 16, v23
	v_add_f32_e32 v30, v30, v22
	v_fmac_f32_e32 v31, v26, v26
	v_and_b32_e32 v23, 0xffff0000, v23
	v_add_f32_e32 v22, v30, v27
	v_fmac_f32_e32 v31, v27, v27
	v_lshlrev_b32_e32 v28, 16, v24
	v_add_f32_e32 v22, v22, v23
	v_fmac_f32_e32 v31, v23, v23
	v_and_b32_e32 v24, 0xffff0000, v24
	v_add_f32_e32 v22, v22, v28
	v_fmac_f32_e32 v31, v28, v28
	v_lshlrev_b32_e32 v29, 16, v25
	v_add_f32_e32 v22, v22, v24
	v_fmac_f32_e32 v31, v24, v24
	v_and_b32_e32 v25, 0xffff0000, v25
	v_add_f32_e32 v22, v22, v29
	v_fmac_f32_e32 v31, v29, v29
	v_add_f32_e32 v22, v22, v25
	v_fmac_f32_e32 v31, v25, v25
	s_nop 0
	v_add_f32_dpp v22, v22, v22 row_ror:1 row_mask:0xf bank_mask:0xf bound_ctrl:1
	v_add_f32_dpp v24, v31, v31 row_ror:1 row_mask:0xf bank_mask:0xf bound_ctrl:1
	s_nop 0
	v_add_f32_dpp v22, v22, v22 row_ror:2 row_mask:0xf bank_mask:0xf bound_ctrl:1
	v_add_f32_dpp v24, v24, v24 row_ror:2 row_mask:0xf bank_mask:0xf bound_ctrl:1
	s_nop 0
	v_add_f32_dpp v22, v22, v22 row_ror:4 row_mask:0xf bank_mask:0xf bound_ctrl:1
	v_add_f32_dpp v24, v24, v24 row_ror:4 row_mask:0xf bank_mask:0xf bound_ctrl:1
	s_nop 0
	v_add_f32_dpp v22, v22, v22 row_ror:8 row_mask:0xf bank_mask:0xf bound_ctrl:1
	v_add_f32_dpp v24, v24, v24 row_ror:8 row_mask:0xf bank_mask:0xf bound_ctrl:1
	v_mov_b32_e32 v23, v22
	v_mov_b32_e32 v25, v24
	s_nop 0
	v_permlane16_swap_b32_e32 v22, v23
	v_permlane16_swap_b32_e32 v24, v25
	v_add_f32_e32 v22, v22, v23
	v_add_f32_e32 v24, v24, v25
	v_mov_b32_e32 v23, v22
	v_mov_b32_e32 v25, v24
	s_nop 0
	v_permlane32_swap_b32_e32 v22, v23
	v_permlane32_swap_b32_e32 v24, v25
	s_and_saveexec_b64 s[6:7], vcc
	s_cbranch_execz .LBB0_518
	v_add_f32_e32 v22, v22, v23
	v_mul_f32_e32 v22, 0x3b000000, v22
	v_add_f32_e32 v24, v24, v25
	v_mul_f32_e32 v23, v22, v22
	v_fma_f32 v23, v24, s4, -v23
	v_max_f32_e32 v23, 0, v23
	v_add_f32_e32 v23, 0x358637bd, v23
	v_rsq_f32_e32 v23, v23
	s_add_i32 s11, s10, 0
	s_add_i32 s11, s11, 0x12850
	v_mov_b32_e32 v24, s11
	ds_write_b64 v24, v[22:23]
.LBB0_518:
	s_or_b64 exec, exec, s[6:7]
	s_waitcnt vmcnt(20)
	v_lshlrev_b32_e32 v22, 16, v18
	v_and_b32_e32 v18, 0xffff0000, v18
	v_add_f32_e32 v26, 0, v22
	v_mul_f32_e32 v27, v18, v18
	v_lshlrev_b32_e32 v23, 16, v19
	v_add_f32_e32 v26, v26, v18
	v_fmac_f32_e32 v27, v22, v22
	v_and_b32_e32 v19, 0xffff0000, v19
	v_add_f32_e32 v18, v26, v23
	v_fmac_f32_e32 v27, v23, v23
	v_lshlrev_b32_e32 v24, 16, v20
	v_add_f32_e32 v18, v18, v19
	v_fmac_f32_e32 v27, v19, v19
	v_and_b32_e32 v20, 0xffff0000, v20
	v_add_f32_e32 v18, v18, v24
	v_fmac_f32_e32 v27, v24, v24
	v_lshlrev_b32_e32 v25, 16, v21
	v_add_f32_e32 v18, v18, v20
	v_fmac_f32_e32 v27, v20, v20
	v_and_b32_e32 v21, 0xffff0000, v21
	v_add_f32_e32 v18, v18, v25
	v_fmac_f32_e32 v27, v25, v25
	v_add_f32_e32 v18, v18, v21
	v_fmac_f32_e32 v27, v21, v21
	s_nop 0
	v_add_f32_dpp v18, v18, v18 row_ror:1 row_mask:0xf bank_mask:0xf bound_ctrl:1
	v_add_f32_dpp v20, v27, v27 row_ror:1 row_mask:0xf bank_mask:0xf bound_ctrl:1
	s_nop 0
	v_add_f32_dpp v18, v18, v18 row_ror:2 row_mask:0xf bank_mask:0xf bound_ctrl:1
	v_add_f32_dpp v20, v20, v20 row_ror:2 row_mask:0xf bank_mask:0xf bound_ctrl:1
	s_nop 0
	v_add_f32_dpp v18, v18, v18 row_ror:4 row_mask:0xf bank_mask:0xf bound_ctrl:1
	v_add_f32_dpp v20, v20, v20 row_ror:4 row_mask:0xf bank_mask:0xf bound_ctrl:1
	s_nop 0
	v_add_f32_dpp v18, v18, v18 row_ror:8 row_mask:0xf bank_mask:0xf bound_ctrl:1
	v_add_f32_dpp v20, v20, v20 row_ror:8 row_mask:0xf bank_mask:0xf bound_ctrl:1
	v_mov_b32_e32 v19, v18
	v_mov_b32_e32 v21, v20
	s_nop 0
	v_permlane16_swap_b32_e32 v18, v19
	v_permlane16_swap_b32_e32 v20, v21
	v_add_f32_e32 v18, v18, v19
	v_add_f32_e32 v20, v20, v21
	v_mov_b32_e32 v19, v18
	v_mov_b32_e32 v21, v20
	s_nop 0
	v_permlane32_swap_b32_e32 v18, v19
	v_permlane32_swap_b32_e32 v20, v21
	s_and_saveexec_b64 s[6:7], vcc
	s_cbranch_execz .LBB0_520
	v_add_f32_e32 v18, v18, v19
	v_mul_f32_e32 v18, 0x3b000000, v18
	v_add_f32_e32 v20, v20, v21
	v_mul_f32_e32 v19, v18, v18
	v_fma_f32 v19, v20, s4, -v19
	v_max_f32_e32 v19, 0, v19
	v_add_f32_e32 v19, 0x358637bd, v19
	v_rsq_f32_e32 v19, v19
	s_add_i32 s11, s10, 0
	s_add_i32 s11, s11, 0x12858
	v_mov_b32_e32 v20, s11
	ds_write_b64 v20, v[18:19]
.LBB0_520:
	s_or_b64 exec, exec, s[6:7]
	s_waitcnt vmcnt(19)
	v_lshlrev_b32_e32 v18, 16, v14
	v_and_b32_e32 v14, 0xffff0000, v14
	v_add_f32_e32 v22, 0, v18
	v_mul_f32_e32 v23, v14, v14
	v_lshlrev_b32_e32 v19, 16, v15
	v_add_f32_e32 v22, v22, v14
	v_fmac_f32_e32 v23, v18, v18
	v_and_b32_e32 v15, 0xffff0000, v15
	v_add_f32_e32 v14, v22, v19
	v_fmac_f32_e32 v23, v19, v19
	v_lshlrev_b32_e32 v20, 16, v16
	v_add_f32_e32 v14, v14, v15
	v_fmac_f32_e32 v23, v15, v15
	v_and_b32_e32 v16, 0xffff0000, v16
	v_add_f32_e32 v14, v14, v20
	v_fmac_f32_e32 v23, v20, v20
	v_lshlrev_b32_e32 v21, 16, v17
	v_add_f32_e32 v14, v14, v16
	v_fmac_f32_e32 v23, v16, v16
	v_and_b32_e32 v17, 0xffff0000, v17
	v_add_f32_e32 v14, v14, v21
	v_fmac_f32_e32 v23, v21, v21
	v_add_f32_e32 v14, v14, v17
	v_fmac_f32_e32 v23, v17, v17
	s_nop 0
	v_add_f32_dpp v14, v14, v14 row_ror:1 row_mask:0xf bank_mask:0xf bound_ctrl:1
	v_add_f32_dpp v16, v23, v23 row_ror:1 row_mask:0xf bank_mask:0xf bound_ctrl:1
	s_nop 0
	v_add_f32_dpp v14, v14, v14 row_ror:2 row_mask:0xf bank_mask:0xf bound_ctrl:1
	v_add_f32_dpp v16, v16, v16 row_ror:2 row_mask:0xf bank_mask:0xf bound_ctrl:1
	s_nop 0
	v_add_f32_dpp v14, v14, v14 row_ror:4 row_mask:0xf bank_mask:0xf bound_ctrl:1
	v_add_f32_dpp v16, v16, v16 row_ror:4 row_mask:0xf bank_mask:0xf bound_ctrl:1
	s_nop 0
	v_add_f32_dpp v14, v14, v14 row_ror:8 row_mask:0xf bank_mask:0xf bound_ctrl:1
	v_add_f32_dpp v16, v16, v16 row_ror:8 row_mask:0xf bank_mask:0xf bound_ctrl:1
	v_mov_b32_e32 v15, v14
	v_mov_b32_e32 v17, v16
	s_nop 0
	v_permlane16_swap_b32_e32 v14, v15
	v_permlane16_swap_b32_e32 v16, v17
	v_add_f32_e32 v14, v14, v15
	v_add_f32_e32 v16, v16, v17
	v_mov_b32_e32 v15, v14
	v_mov_b32_e32 v17, v16
	s_nop 0
	v_permlane32_swap_b32_e32 v14, v15
	v_permlane32_swap_b32_e32 v16, v17
	s_and_saveexec_b64 s[6:7], vcc
	s_cbranch_execz .LBB0_522
	v_add_f32_e32 v14, v14, v15
	v_mul_f32_e32 v14, 0x3b000000, v14
	v_add_f32_e32 v16, v16, v17
	v_mul_f32_e32 v15, v14, v14
	v_fma_f32 v15, v16, s4, -v15
	v_max_f32_e32 v15, 0, v15
	v_add_f32_e32 v15, 0x358637bd, v15
	v_rsq_f32_e32 v15, v15
	s_add_i32 s11, s10, 0
	s_add_i32 s11, s11, 0x12860
	v_mov_b32_e32 v16, s11
	ds_write_b64 v16, v[14:15]
; DI float bflo(unsigned w) { return __uint_as_float(w << 16); }
; DI float bfhi(unsigned w) { return __uint_as_float(w & 0xffff0000u); }
; DI void gmlp_unit(LAS char* lds, bf16_t* zU, const bf16_t* zV, const float* g_ln, const float* b_ln, const bf16_t* Wb, const float* b_sp, int R0, bool dummy = false) {
;     ...
;       for (int i = 0; i < 16; ++i) { const int s = wid * 16 + i; const u32x4 w = rw[i];
;         const float v[8] = {bflo(w.x), bfhi(w.x), bflo(w.y), bfhi(w.y), bflo(w.z), bfhi(w.z), bflo(w.w), bfhi(w.w)};
;         float a = 0.f, q = 0.f;
; #pragma unroll
;         for (int e = 0; e < 8; ++e) { a += v[e]; q += v[e] * v[e]; }
;         a = wave_sum(a); q = wave_sum(q);
;         const float mu = a * (1.0f / 512.0f), var = fmaxf(q * (1.0f / 512.0f) - mu * mu, 0.f);
;         if (lane == 0) { St[2 * s] = mu; St[2 * s + 1] = __builtin_amdgcn_rsqf(var + EPSN); } } }
.LBB0_522:
	s_or_b64 exec, exec, s[6:7]
	s_waitcnt vmcnt(18)
	v_lshlrev_b32_e32 v14, 16, v10
	v_and_b32_e32 v10, 0xffff0000, v10
	v_add_f32_e32 v18, 0, v14
	v_mul_f32_e32 v19, v10, v10
	v_lshlrev_b32_e32 v15, 16, v11
	v_add_f32_e32 v18, v18, v10
	v_fmac_f32_e32 v19, v14, v14
	v_and_b32_e32 v11, 0xffff0000, v11
	v_add_f32_e32 v10, v18, v15
	v_fmac_f32_e32 v19, v15, v15
	v_lshlrev_b32_e32 v16, 16, v12
	v_add_f32_e32 v10, v10, v11
	v_fmac_f32_e32 v19, v11, v11
	v_and_b32_e32 v12, 0xffff0000, v12
	v_add_f32_e32 v10, v10, v16
	v_fmac_f32_e32 v19, v16, v16
	v_lshlrev_b32_e32 v17, 16, v13
	v_add_f32_e32 v10, v10, v12
	v_fmac_f32_e32 v19, v12, v12
	v_and_b32_e32 v13, 0xffff0000, v13
	v_add_f32_e32 v10, v10, v17
	v_fmac_f32_e32 v19, v17, v17
	v_add_f32_e32 v10, v10, v13
	v_fmac_f32_e32 v19, v13, v13
	s_nop 0
	v_add_f32_dpp v10, v10, v10 row_ror:1 row_mask:0xf bank_mask:0xf bound_ctrl:1
	v_add_f32_dpp v12, v19, v19 row_ror:1 row_mask:0xf bank_mask:0xf bound_ctrl:1
	s_nop 0
	v_add_f32_dpp v10, v10, v10 row_ror:2 row_mask:0xf bank_mask:0xf bound_ctrl:1
	v_add_f32_dpp v12, v12, v12 row_ror:2 row_mask:0xf bank_mask:0xf bound_ctrl:1
	s_nop 0
	v_add_f32_dpp v10, v10, v10 row_ror:4 row_mask:0xf bank_mask:0xf bound_ctrl:1
	v_add_f32_dpp v12, v12, v12 row_ror:4 row_mask:0xf bank_mask:0xf bound_ctrl:1
	s_nop 0
	v_add_f32_dpp v10, v10, v10 row_ror:8 row_mask:0xf bank_mask:0xf bound_ctrl:1
	v_add_f32_dpp v12, v12, v12 row_ror:8 row_mask:0xf bank_mask:0xf bound_ctrl:1
	v_mov_b32_e32 v11, v10
	v_mov_b32_e32 v13, v12
	s_nop 0
	v_permlane16_swap_b32_e32 v10, v11
	v_permlane16_swap_b32_e32 v12, v13
	v_add_f32_e32 v10, v10, v11
	v_add_f32_e32 v12, v12, v13
	v_mov_b32_e32 v11, v10
	v_mov_b32_e32 v13, v12
	s_nop 0
	v_permlane32_swap_b32_e32 v10, v11
	v_permlane32_swap_b32_e32 v12, v13
	s_and_saveexec_b64 s[6:7], vcc
	s_cbranch_execz .LBB0_524
	v_add_f32_e32 v10, v10, v11
	v_mul_f32_e32 v10, 0x3b000000, v10
	v_add_f32_e32 v12, v12, v13
	v_mul_f32_e32 v11, v10, v10
	v_fma_f32 v11, v12, s4, -v11
	v_max_f32_e32 v11, 0, v11
	v_add_f32_e32 v11, 0x358637bd, v11
	v_rsq_f32_e32 v11, v11
	s_add_i32 s11, s10, 0
	s_add_i32 s11, s11, 0x12868
	v_mov_b32_e32 v12, s11
	ds_write_b64 v12, v[10:11]
.LBB0_524:
	s_or_b64 exec, exec, s[6:7]
	s_waitcnt vmcnt(17)
	v_lshlrev_b32_e32 v10, 16, v6
	v_and_b32_e32 v6, 0xffff0000, v6
	v_add_f32_e32 v14, 0, v10
	v_mul_f32_e32 v15, v6, v6
	v_lshlrev_b32_e32 v11, 16, v7
	v_add_f32_e32 v14, v14, v6
	v_fmac_f32_e32 v15, v10, v10
	v_and_b32_e32 v7, 0xffff0000, v7
	v_add_f32_e32 v6, v14, v11
	v_fmac_f32_e32 v15, v11, v11
	v_lshlrev_b32_e32 v12, 16, v8
	v_add_f32_e32 v6, v6, v7
	v_fmac_f32_e32 v15, v7, v7
	v_and_b32_e32 v8, 0xffff0000, v8
	v_add_f32_e32 v6, v6, v12
	v_fmac_f32_e32 v15, v12, v12
	v_lshlrev_b32_e32 v13, 16, v9
	v_add_f32_e32 v6, v6, v8
	v_fmac_f32_e32 v15, v8, v8
	v_and_b32_e32 v9, 0xffff0000, v9
	v_add_f32_e32 v6, v6, v13
	v_fmac_f32_e32 v15, v13, v13
	v_add_f32_e32 v6, v6, v9
	v_fmac_f32_e32 v15, v9, v9
	s_nop 0
	v_add_f32_dpp v6, v6, v6 row_ror:1 row_mask:0xf bank_mask:0xf bound_ctrl:1
	v_add_f32_dpp v8, v15, v15 row_ror:1 row_mask:0xf bank_mask:0xf bound_ctrl:1
	s_nop 0
	v_add_f32_dpp v6, v6, v6 row_ror:2 row_mask:0xf bank_mask:0xf bound_ctrl:1
	v_add_f32_dpp v8, v8, v8 row_ror:2 row_mask:0xf bank_mask:0xf bound_ctrl:1
	s_nop 0
	v_add_f32_dpp v6, v6, v6 row_ror:4 row_mask:0xf bank_mask:0xf bound_ctrl:1
	v_add_f32_dpp v8, v8, v8 row_ror:4 row_mask:0xf bank_mask:0xf bound_ctrl:1
	s_nop 0
	v_add_f32_dpp v6, v6, v6 row_ror:8 row_mask:0xf bank_mask:0xf bound_ctrl:1
	v_add_f32_dpp v8, v8, v8 row_ror:8 row_mask:0xf bank_mask:0xf bound_ctrl:1
	v_mov_b32_e32 v7, v6
	v_mov_b32_e32 v9, v8
	s_nop 0
	v_permlane16_swap_b32_e32 v6, v7
	v_permlane16_swap_b32_e32 v8, v9
	v_add_f32_e32 v6, v6, v7
	v_add_f32_e32 v8, v8, v9
	v_mov_b32_e32 v7, v6
	v_mov_b32_e32 v9, v8
	s_nop 0
	v_permlane32_swap_b32_e32 v6, v7
	v_permlane32_swap_b32_e32 v8, v9
	s_and_saveexec_b64 s[6:7], vcc
	s_cbranch_execz .LBB0_526
	v_add_f32_e32 v6, v6, v7
	v_mul_f32_e32 v6, 0x3b000000, v6
	v_add_f32_e32 v8, v8, v9
	v_mul_f32_e32 v7, v6, v6
	v_fma_f32 v7, v8, s4, -v7
	v_max_f32_e32 v7, 0, v7
	v_add_f32_e32 v7, 0x358637bd, v7
	v_rsq_f32_e32 v7, v7
	s_add_i32 s11, s10, 0
	s_add_i32 s11, s11, 0x12870
	v_mov_b32_e32 v8, s11
	ds_write_b64 v8, v[6:7]
.LBB0_526:
	s_or_b64 exec, exec, s[6:7]
	s_waitcnt vmcnt(16)
	v_lshlrev_b32_e32 v6, 16, v2
	v_and_b32_e32 v2, 0xffff0000, v2
	v_add_f32_e32 v10, 0, v6
	v_mul_f32_e32 v11, v2, v2
	v_lshlrev_b32_e32 v7, 16, v3
	v_add_f32_e32 v10, v10, v2
	v_fmac_f32_e32 v11, v6, v6
	v_and_b32_e32 v3, 0xffff0000, v3
	v_add_f32_e32 v2, v10, v7
	v_fmac_f32_e32 v11, v7, v7
	v_lshlrev_b32_e32 v8, 16, v4
	v_add_f32_e32 v2, v2, v3
	v_fmac_f32_e32 v11, v3, v3
	v_and_b32_e32 v4, 0xffff0000, v4
	v_add_f32_e32 v2, v2, v8
	v_fmac_f32_e32 v11, v8, v8
	v_lshlrev_b32_e32 v9, 16, v5
	v_add_f32_e32 v2, v2, v4
	v_fmac_f32_e32 v11, v4, v4
	v_and_b32_e32 v5, 0xffff0000, v5
	v_add_f32_e32 v2, v2, v9
	v_fmac_f32_e32 v11, v9, v9
	v_add_f32_e32 v2, v2, v5
	v_fmac_f32_e32 v11, v5, v5
	s_nop 0
	v_add_f32_dpp v2, v2, v2 row_ror:1 row_mask:0xf bank_mask:0xf bound_ctrl:1
	v_add_f32_dpp v4, v11, v11 row_ror:1 row_mask:0xf bank_mask:0xf bound_ctrl:1
	s_nop 0
	v_add_f32_dpp v2, v2, v2 row_ror:2 row_mask:0xf bank_mask:0xf bound_ctrl:1
	v_add_f32_dpp v4, v4, v4 row_ror:2 row_mask:0xf bank_mask:0xf bound_ctrl:1
	s_nop 0
	v_add_f32_dpp v2, v2, v2 row_ror:4 row_mask:0xf bank_mask:0xf bound_ctrl:1
	v_add_f32_dpp v4, v4, v4 row_ror:4 row_mask:0xf bank_mask:0xf bound_ctrl:1
	s_nop 0
	v_add_f32_dpp v2, v2, v2 row_ror:8 row_mask:0xf bank_mask:0xf bound_ctrl:1
	v_add_f32_dpp v4, v4, v4 row_ror:8 row_mask:0xf bank_mask:0xf bound_ctrl:1
	v_mov_b32_e32 v3, v2
	v_mov_b32_e32 v5, v4
	s_nop 0
	v_permlane16_swap_b32_e32 v2, v3
	v_permlane16_swap_b32_e32 v4, v5
	v_add_f32_e32 v2, v2, v3
	v_add_f32_e32 v4, v4, v5
	v_mov_b32_e32 v3, v2
	v_mov_b32_e32 v5, v4
	s_nop 0
	v_permlane32_swap_b32_e32 v2, v3
	v_permlane32_swap_b32_e32 v4, v5
	s_and_saveexec_b64 s[6:7], vcc
	s_cbranch_execz .LBB0_528
	v_add_f32_e32 v2, v2, v3
	v_mul_f32_e32 v2, 0x3b000000, v2
	v_add_f32_e32 v4, v4, v5
	v_mul_f32_e32 v3, v2, v2
	v_fma_f32 v3, v4, s4, -v3
	v_max_f32_e32 v3, 0, v3
	v_add_f32_e32 v3, 0x358637bd, v3
	v_rsq_f32_e32 v3, v3
	s_add_i32 s10, s10, 0
	s_add_i32 s10, s10, 0x12878
	v_mov_b32_e32 v4, s10
	ds_write_b64 v4, v[2:3]

; __global__ void __launch_bounds__(512) mega_fwd(Args a_unused) {
	.amdhsa_kernel _Z8mega_fwd4Args
		.amdhsa_group_segment_fixed_size 0
		.amdhsa_private_segment_fixed_size 0
		.amdhsa_kernarg_size 496
		.amdhsa_user_sgpr_count 2
		.amdhsa_user_sgpr_dispatch_ptr 0
		.amdhsa_user_sgpr_queue_ptr 0
		.amdhsa_user_sgpr_kernarg_segment_ptr 1
		.amdhsa_user_sgpr_dispatch_id 0
		.amdhsa_user_sgpr_kernarg_preload_length 0
		.amdhsa_user_sgpr_kernarg_preload_offset 0
		.amdhsa_user_sgpr_private_segment_size 0
		.amdhsa_uses_dynamic_stack 0
		.amdhsa_enable_private_segment 0
		.amdhsa_system_sgpr_workgroup_id_x 1
		.amdhsa_system_sgpr_workgroup_id_y 0
		.amdhsa_system_sgpr_workgroup_id_z 0
		.amdhsa_system_sgpr_workgroup_info 0
		.amdhsa_system_vgpr_workitem_id 2
		.amdhsa_next_free_vgpr 254
		.amdhsa_next_free_sgpr 100
		.amdhsa_accum_offset 256
		.amdhsa_reserve_vcc 1
		.amdhsa_float_round_mode_32 0
		.amdhsa_float_round_mode_16_64 0
		.amdhsa_float_denorm_mode_32 3
		.amdhsa_float_denorm_mode_16_64 3
		.amdhsa_dx10_clamp 1
		.amdhsa_ieee_mode 1
		.amdhsa_fp16_overflow 0
		.amdhsa_tg_split 0
		.amdhsa_exception_fp_ieee_invalid_op 0
		.amdhsa_exception_fp_denorm_src 0
		.amdhsa_exception_fp_ieee_div_zero 0
		.amdhsa_exception_fp_ieee_overflow 0
		.amdhsa_exception_fp_ieee_underflow 0
		.amdhsa_exception_fp_ieee_inexact 0
		.amdhsa_exception_int_div_zero 0
	.end_amdhsa_kernel

; __global__ void __launch_bounds__(512) mega_fwd(Args a_unused) {
amdhsa.kernels:
  - .agpr_count:     0
    .args:
      - .offset:         0
        .size:           240
        .value_kind:     by_value
      - .offset:         240
        .size:           4
        .value_kind:     hidden_block_count_x
      - .offset:         244
        .size:           4
        .value_kind:     hidden_block_count_y
      - .offset:         248
        .size:           4
        .value_kind:     hidden_block_count_z
      - .offset:         252
        .size:           2
        .value_kind:     hidden_group_size_x
      - .offset:         254
        .size:           2
        .value_kind:     hidden_group_size_y
      - .offset:         256
        .size:           2
        .value_kind:     hidden_group_size_z
      - .offset:         258
        .size:           2
        .value_kind:     hidden_remainder_x
      - .offset:         260
        .size:           2
        .value_kind:     hidden_remainder_y
      - .offset:         262
        .size:           2
        .value_kind:     hidden_remainder_z
      - .offset:         280
        .size:           8
        .value_kind:     hidden_global_offset_x
      - .offset:         288
        .size:           8
        .value_kind:     hidden_global_offset_y
      - .offset:         296
        .size:           8
        .value_kind:     hidden_global_offset_z
      - .offset:         304
        .size:           2
        .value_kind:     hidden_grid_dims
      - .offset:         328
        .size:           8
        .value_kind:     hidden_multigrid_sync_arg
      - .offset:         360
        .size:           4
        .value_kind:     hidden_dynamic_lds_size
    .group_segment_fixed_size: 0
    .kernarg_segment_align: 8
    .kernarg_segment_size: 496
    .language:       OpenCL C
    .language_version:
      - 2
      - 0
    .max_flat_workgroup_size: 512
    .name:           _Z8mega_fwd4Args
    .private_segment_fixed_size: 0
    .sgpr_count:     106
    .sgpr_spill_count: 45
    .symbol:         _Z8mega_fwd4Args.kd
    .uniform_work_group_size: 1
    .uses_dynamic_stack: false
    .vgpr_count:     254
    .vgpr_spill_count: 0
    .wavefront_size: 64
